# P10 final f32 output stores through cross-wave LDS exchange so each store instruction writes one full contiguous 1KB row; on top of P6 pass-2 and P8 row-stores
# speedup vs baseline: 1.0062x; 1.0062x over previous
.LBB0_1887:
	s_or_b64 exec, exec, s[0:1]
	v_lshlrev_b64 v[72:73], 2, v[176:177]
	v_lshl_add_u64 v[0:1], s[74:75], 0, v[72:73]
	s_waitcnt lgkmcnt(0)
	s_barrier
	v_and_b32_e32 v238, 7, v181
	v_lshrrev_b32_e32 v239, 7, v181
	v_bfe_u32 v240, v176, 6, 2
	v_and_b32_e32 v241, 56, v176
	v_lshl_add_u32 v242, v239, 3, v238
	v_mul_u32_u24_e32 v242, 0x410, v242
	v_lshl_add_u32 v242, v240, 8, v242
	v_lshl_add_u32 v242, v241, 2, v242
	v_add_u32_e32 v224, 0x12000, v242
	v_lshl_add_u32 v243, v239, 2, v240
	v_lshrrev_b32_e32 v244, 3, v241
	v_lshl_add_u32 v244, v238, 3, v244
	v_mul_u32_u24_e32 v243, 0x820, v243
	v_lshl_add_u32 v243, v244, 4, v243
	v_add_u32_e32 v225, 0x12000, v243
	v_lshlrev_b32_e32 v245, 1, v240
	v_sub_u32_e32 v245, v245, v238
	v_lshlrev_b32_e32 v245, 12, v245
	v_lshlrev_b32_e32 v244, 2, v244
	v_lshlrev_b32_e32 v240, 6, v240
	v_sub_u32_e32 v244, v244, v240
	v_sub_u32_e32 v244, v244, v241
	v_lshl_add_u32 v226, v244, 2, v245
	v_add_u32_e32 v226, 0x800, v226
	v_ashrrev_i32_e32 v227, 31, v226
	global_load_dwordx4 v[4:7], v[0:1], off
	s_nop 0
	global_load_dwordx4 v[0:3], v[0:1], off offset:16
	v_or_b32_e32 v79, 16, v181
	s_add_i32 s0, 0, 0x25000
	v_or_b32_e32 v97, 24, v181
	v_add_u32_e32 v96, s14, v79
	v_add_u32_e32 v74, s14, v181
	v_or_b32_e32 v77, 8, v181
	v_lshl_add_u32 v101, v97, 2, s0
	v_add_u32_e32 v130, s14, v97
	v_ashrrev_i32_e32 v97, 31, v96
	v_or_b32_e32 v133, 48, v181
	v_or_b32_e32 v135, 56, v181
	v_ashrrev_i32_e32 v75, 31, v74
	v_add_u32_e32 v78, s14, v77
	v_lshlrev_b64 v[96:97], 12, v[96:97]
	v_or_b32_e32 v109, 40, v181
	v_lshl_add_u32 v98, v181, 2, s0
	v_lshl_add_u32 v99, v77, 2, s0
	v_lshl_add_u32 v77, v79, 2, s0
	v_lshl_add_u32 v106, v133, 2, s0
	v_lshl_add_u32 v107, v135, 2, s0
	v_lshlrev_b64 v[74:75], 12, v[74:75]
	v_ashrrev_i32_e32 v79, 31, v78
	v_lshl_add_u64 v[96:97], s[76:77], 0, v[96:97]
	v_lshl_add_u32 v103, v168, 2, s0
	v_lshl_add_u32 v105, v109, 2, s0
	ds_read_b32 v98, v98
	ds_read_b32 v100, v99
	ds_read_b32 v102, v77
	ds_read_b32 v104, v101
	ds_read_b32 v132, v103
	ds_read_b32 v134, v105
	ds_read_b32 v170, v106
	ds_read_b32 v172, v107
	v_lshl_add_u64 v[74:75], s[76:77], 0, v[74:75]
	v_lshlrev_b64 v[78:79], 12, v[78:79]
	v_lshl_add_u64 v[174:175], v[96:97], 0, v[72:73]
	s_waitcnt lgkmcnt(7)
	v_pk_mul_f32 v[96:97], v[112:113], v[98:99] op_sel_hi:[1,0]
	v_pk_mul_f32 v[106:107], v[114:115], v[98:99] op_sel_hi:[1,0]
	v_lshl_add_u64 v[74:75], v[74:75], 0, v[72:73]
	v_lshl_add_u64 v[78:79], s[76:77], 0, v[78:79]
	v_pk_mul_f32 v[110:111], v[116:117], v[98:99] op_sel_hi:[1,0]
	v_pk_mul_f32 v[112:113], v[118:119], v[98:99] op_sel_hi:[1,0]
	s_waitcnt lgkmcnt(6)
	v_pk_mul_f32 v[114:115], v[120:121], v[100:101] op_sel_hi:[1,0]
	v_pk_mul_f32 v[116:117], v[122:123], v[100:101] op_sel_hi:[1,0]
	v_pk_mul_f32 v[118:119], v[124:125], v[100:101] op_sel_hi:[1,0]
	v_pk_mul_f32 v[120:121], v[126:127], v[100:101] op_sel_hi:[1,0]
	s_waitcnt lgkmcnt(5)
	v_pk_mul_f32 v[122:123], v[160:161], v[102:103] op_sel_hi:[1,0]
	v_pk_mul_f32 v[124:125], v[156:157], v[102:103] op_sel_hi:[1,0]
	v_pk_mul_f32 v[126:127], v[162:163], v[102:103] op_sel_hi:[1,0]
	v_pk_mul_f32 v[128:129], v[158:159], v[102:103] op_sel_hi:[1,0]
	v_ashrrev_i32_e32 v131, 31, v130
	v_lshl_add_u64 v[78:79], v[78:79], 0, v[72:73]
	s_waitcnt lgkmcnt(4)
	v_pk_mul_f32 v[156:157], v[164:165], v[104:105] op_sel_hi:[1,0]
	v_pk_mul_f32 v[152:153], v[152:153], v[104:105] op_sel_hi:[1,0]
	v_pk_mul_f32 v[158:159], v[166:167], v[104:105] op_sel_hi:[1,0]
	v_pk_mul_f32 v[154:155], v[154:155], v[104:105] op_sel_hi:[1,0]
	v_or_b32_e32 v77, 0x48, v181
	s_add_i32 s49, s49, s33
	s_cmpk_gt_i32 s49, 0x1ff
	s_waitcnt vmcnt(1)
	v_pk_mul_f32 v[98:99], v[6:7], v[106:107]
	v_pk_mul_f32 v[96:97], v[4:5], v[96:97]
	s_waitcnt vmcnt(0)
	v_pk_mul_f32 v[102:103], v[2:3], v[112:113]
	v_pk_mul_f32 v[100:101], v[0:1], v[110:111]
	v_pk_mul_f32 v[106:107], v[6:7], v[116:117]
	v_pk_mul_f32 v[104:105], v[4:5], v[114:115]
	v_pk_mul_f32 v[112:113], v[2:3], v[120:121]
	v_pk_mul_f32 v[110:111], v[0:1], v[118:119]
	v_pk_mul_f32 v[116:117], v[6:7], v[124:125]
	v_pk_mul_f32 v[114:115], v[4:5], v[122:123]
	v_pk_mul_f32 v[120:121], v[2:3], v[128:129]
	v_pk_mul_f32 v[118:119], v[0:1], v[126:127]
	ds_write_b128 v224, v[96:99]
	ds_write_b128 v224, v[100:103] offset:16
	v_lshl_add_u64 v[228:229], v[74:75], 0, v[226:227]
	s_waitcnt lgkmcnt(0)
	s_barrier
	ds_read_b128 v[230:233], v225
	ds_read_b128 v[234:237], v225 offset:1040
	s_waitcnt lgkmcnt(0)
	s_barrier
	global_store_dwordx4 v[228:229], v[230:233], off offset:-2048
	global_store_dwordx4 v[228:229], v[234:237], off offset:2048
	ds_write_b128 v224, v[104:107]
	ds_write_b128 v224, v[110:113] offset:16
	v_lshl_add_u64 v[228:229], v[78:79], 0, v[226:227]
	s_waitcnt lgkmcnt(0)
	s_barrier
	ds_read_b128 v[230:233], v225
	ds_read_b128 v[234:237], v225 offset:1040
	s_waitcnt lgkmcnt(0)
	s_barrier
	global_store_dwordx4 v[228:229], v[230:233], off offset:-2048
	global_store_dwordx4 v[228:229], v[234:237], off offset:2048
	ds_write_b128 v224, v[114:117]
	ds_write_b128 v224, v[118:121] offset:16
	v_lshl_add_u64 v[228:229], v[174:175], 0, v[226:227]
	s_waitcnt lgkmcnt(0)
	s_barrier
	ds_read_b128 v[230:233], v225
	ds_read_b128 v[234:237], v225 offset:1040
	s_waitcnt lgkmcnt(0)
	s_barrier
	global_store_dwordx4 v[228:229], v[230:233], off offset:-2048
	global_store_dwordx4 v[228:229], v[234:237], off offset:2048
	v_lshlrev_b64 v[74:75], 12, v[130:131]
	v_lshl_add_u64 v[74:75], s[76:77], 0, v[74:75]
	v_pk_mul_f32 v[124:125], v[6:7], v[152:153]
	v_pk_mul_f32 v[122:123], v[4:5], v[156:157]
	v_lshl_add_u64 v[74:75], v[74:75], 0, v[72:73]
	v_pk_mul_f32 v[128:129], v[2:3], v[154:155]
	v_pk_mul_f32 v[126:127], v[0:1], v[158:159]
	ds_write_b128 v224, v[122:125]
	ds_write_b128 v224, v[126:129] offset:16
	v_lshl_add_u64 v[228:229], v[74:75], 0, v[226:227]
	s_waitcnt lgkmcnt(0)
	s_barrier
	ds_read_b128 v[230:233], v225
	ds_read_b128 v[234:237], v225 offset:1040
	s_waitcnt lgkmcnt(0)
	s_barrier
	global_store_dwordx4 v[228:229], v[230:233], off offset:-2048
	global_store_dwordx4 v[228:229], v[234:237], off offset:2048
	v_add_u32_e32 v74, s14, v168
	v_ashrrev_i32_e32 v75, 31, v74
	v_lshlrev_b64 v[74:75], 12, v[74:75]
	s_waitcnt lgkmcnt(3)
	v_pk_mul_f32 v[78:79], v[80:81], v[132:133] op_sel_hi:[1,0]
	v_pk_mul_f32 v[80:81], v[82:83], v[132:133] op_sel_hi:[1,0]
	v_lshl_add_u64 v[74:75], s[76:77], 0, v[74:75]
	v_pk_mul_f32 v[80:81], v[6:7], v[80:81]
	v_pk_mul_f32 v[78:79], v[4:5], v[78:79]
	v_pk_mul_f32 v[82:83], v[84:85], v[132:133] op_sel_hi:[1,0]
	v_pk_mul_f32 v[84:85], v[86:87], v[132:133] op_sel_hi:[1,0]
	v_lshl_add_u64 v[74:75], v[74:75], 0, v[72:73]
	v_pk_mul_f32 v[84:85], v[2:3], v[84:85]
	v_pk_mul_f32 v[82:83], v[0:1], v[82:83]
	ds_write_b128 v224, v[78:81]
	ds_write_b128 v224, v[82:85] offset:16
	v_lshl_add_u64 v[228:229], v[74:75], 0, v[226:227]
	s_waitcnt lgkmcnt(0)
	s_barrier
	ds_read_b128 v[230:233], v225
	ds_read_b128 v[234:237], v225 offset:1040
	s_waitcnt lgkmcnt(0)
	s_barrier
	global_store_dwordx4 v[228:229], v[230:233], off offset:-2048
	global_store_dwordx4 v[228:229], v[234:237], off offset:2048
	v_add_u32_e32 v74, s14, v109
	v_ashrrev_i32_e32 v75, 31, v74
	v_lshlrev_b64 v[74:75], 12, v[74:75]
	s_waitcnt lgkmcnt(2)
	v_pk_mul_f32 v[78:79], v[88:89], v[134:135] op_sel_hi:[1,0]
	v_pk_mul_f32 v[80:81], v[90:91], v[134:135] op_sel_hi:[1,0]
	v_lshl_add_u64 v[74:75], s[76:77], 0, v[74:75]
	v_pk_mul_f32 v[80:81], v[6:7], v[80:81]
	v_pk_mul_f32 v[78:79], v[4:5], v[78:79]
	v_pk_mul_f32 v[82:83], v[92:93], v[134:135] op_sel_hi:[1,0]
	v_pk_mul_f32 v[84:85], v[94:95], v[134:135] op_sel_hi:[1,0]
	v_lshl_add_u64 v[74:75], v[74:75], 0, v[72:73]
	v_pk_mul_f32 v[84:85], v[2:3], v[84:85]
	v_pk_mul_f32 v[82:83], v[0:1], v[82:83]
	ds_write_b128 v224, v[78:81]
	ds_write_b128 v224, v[82:85] offset:16
	v_lshl_add_u64 v[228:229], v[74:75], 0, v[226:227]
	s_waitcnt lgkmcnt(0)
	s_barrier
	ds_read_b128 v[230:233], v225
	ds_read_b128 v[234:237], v225 offset:1040
	s_waitcnt lgkmcnt(0)
	s_barrier
	global_store_dwordx4 v[228:229], v[230:233], off offset:-2048
	global_store_dwordx4 v[228:229], v[234:237], off offset:2048
	v_add_u32_e32 v74, s14, v133
	v_ashrrev_i32_e32 v75, 31, v74
	v_lshlrev_b64 v[74:75], 12, v[74:75]
	s_waitcnt lgkmcnt(1)
	v_pk_mul_f32 v[78:79], v[144:145], v[170:171] op_sel_hi:[1,0]
	v_pk_mul_f32 v[80:81], v[140:141], v[170:171] op_sel_hi:[1,0]
	v_lshl_add_u64 v[74:75], s[76:77], 0, v[74:75]
	v_pk_mul_f32 v[80:81], v[6:7], v[80:81]
	v_pk_mul_f32 v[78:79], v[4:5], v[78:79]
	v_pk_mul_f32 v[82:83], v[146:147], v[170:171] op_sel_hi:[1,0]
	v_pk_mul_f32 v[84:85], v[142:143], v[170:171] op_sel_hi:[1,0]
	v_lshl_add_u64 v[74:75], v[74:75], 0, v[72:73]
	v_pk_mul_f32 v[84:85], v[2:3], v[84:85]
	v_pk_mul_f32 v[82:83], v[0:1], v[82:83]
	ds_write_b128 v224, v[78:81]
	ds_write_b128 v224, v[82:85] offset:16
	v_lshl_add_u64 v[228:229], v[74:75], 0, v[226:227]
	s_waitcnt lgkmcnt(0)
	s_barrier
	ds_read_b128 v[230:233], v225
	ds_read_b128 v[234:237], v225 offset:1040
	s_waitcnt lgkmcnt(0)
	s_barrier
	global_store_dwordx4 v[228:229], v[230:233], off offset:-2048
	global_store_dwordx4 v[228:229], v[234:237], off offset:2048
	v_add_u32_e32 v74, s14, v135
	v_ashrrev_i32_e32 v75, 31, v74
	v_lshlrev_b64 v[74:75], 12, v[74:75]
	s_waitcnt lgkmcnt(0)
	v_pk_mul_f32 v[78:79], v[148:149], v[172:173] op_sel_hi:[1,0]
	v_pk_mul_f32 v[80:81], v[136:137], v[172:173] op_sel_hi:[1,0]
	v_pk_mul_f32 v[82:83], v[150:151], v[172:173] op_sel_hi:[1,0]
	v_lshl_add_u64 v[74:75], s[76:77], 0, v[74:75]
	v_pk_mul_f32 v[80:81], v[6:7], v[80:81]
	v_pk_mul_f32 v[78:79], v[4:5], v[78:79]
	v_pk_mul_f32 v[84:85], v[138:139], v[172:173] op_sel_hi:[1,0]
	v_pk_mul_f32 v[82:83], v[0:1], v[82:83]
	v_lshl_add_u64 v[74:75], v[74:75], 0, v[72:73]
	v_pk_mul_f32 v[84:85], v[2:3], v[84:85]
	ds_write_b128 v224, v[78:81]
	ds_write_b128 v224, v[82:85] offset:16
	v_lshl_add_u64 v[228:229], v[74:75], 0, v[226:227]
	s_waitcnt lgkmcnt(0)
	s_barrier
	ds_read_b128 v[230:233], v225
	ds_read_b128 v[234:237], v225 offset:1040
	s_waitcnt lgkmcnt(0)
	s_barrier
	global_store_dwordx4 v[228:229], v[230:233], off offset:-2048
	global_store_dwordx4 v[228:229], v[234:237], off offset:2048
	v_or_b32_e32 v87, 0x68, v181
	v_or_b32_e32 v81, 0x50, v181
	v_or_b32_e32 v83, 0x58, v181
	v_or_b32_e32 v89, 0x70, v181
	v_or_b32_e32 v91, 0x78, v181
	v_lshl_add_u32 v75, v108, 2, s0
	v_add_u32_e32 v74, s14, v108
	v_lshl_add_u32 v82, v81, 2, s0
	v_lshl_add_u32 v84, v83, 2, s0
	v_lshl_add_u32 v88, v87, 2, s0
	v_lshl_add_u32 v90, v89, 2, s0
	v_lshl_add_u32 v92, v91, 2, s0
	v_lshl_add_u32 v79, v77, 2, s0
	v_lshl_add_u32 v85, v76, 2, s0
	ds_read_b32 v78, v75
	ds_read_b32 v80, v79
	ds_read_b32 v82, v82
	ds_read_b32 v84, v84
	ds_read_b32 v86, v85
	ds_read_b32 v88, v88
	ds_read_b32 v90, v90
	ds_read_b32 v92, v92
	v_ashrrev_i32_e32 v75, 31, v74
	v_lshlrev_b64 v[74:75], 12, v[74:75]
	s_waitcnt lgkmcnt(7)
	v_pk_mul_f32 v[32:33], v[32:33], v[78:79] op_sel_hi:[1,0]
	v_pk_mul_f32 v[34:35], v[34:35], v[78:79] op_sel_hi:[1,0]
	v_lshl_add_u64 v[74:75], s[76:77], 0, v[74:75]
	v_pk_mul_f32 v[34:35], v[6:7], v[34:35]
	v_pk_mul_f32 v[32:33], v[4:5], v[32:33]
	v_pk_mul_f32 v[36:37], v[36:37], v[78:79] op_sel_hi:[1,0]
	v_pk_mul_f32 v[38:39], v[38:39], v[78:79] op_sel_hi:[1,0]
	v_lshl_add_u64 v[74:75], v[74:75], 0, v[72:73]
	v_pk_mul_f32 v[38:39], v[2:3], v[38:39]
	v_pk_mul_f32 v[36:37], v[0:1], v[36:37]
	ds_write_b128 v224, v[32:35]
	ds_write_b128 v224, v[36:39] offset:16
	v_lshl_add_u64 v[228:229], v[74:75], 0, v[226:227]
	s_waitcnt lgkmcnt(0)
	s_barrier
	ds_read_b128 v[230:233], v225
	ds_read_b128 v[234:237], v225 offset:1040
	s_waitcnt lgkmcnt(0)
	s_barrier
	global_store_dwordx4 v[228:229], v[230:233], off offset:-2048
	global_store_dwordx4 v[228:229], v[234:237], off offset:2048
	v_add_u32_e32 v74, s14, v77
	v_ashrrev_i32_e32 v75, 31, v74
	s_waitcnt lgkmcnt(6)
	v_pk_mul_f32 v[32:33], v[40:41], v[80:81] op_sel_hi:[1,0]
	v_lshlrev_b64 v[40:41], 12, v[74:75]
	v_pk_mul_f32 v[34:35], v[42:43], v[80:81] op_sel_hi:[1,0]
	v_lshl_add_u64 v[40:41], s[76:77], 0, v[40:41]
	v_pk_mul_f32 v[34:35], v[6:7], v[34:35]
	v_pk_mul_f32 v[32:33], v[4:5], v[32:33]
	v_pk_mul_f32 v[36:37], v[44:45], v[80:81] op_sel_hi:[1,0]
	v_pk_mul_f32 v[38:39], v[46:47], v[80:81] op_sel_hi:[1,0]
	v_lshl_add_u64 v[40:41], v[40:41], 0, v[72:73]
	v_pk_mul_f32 v[38:39], v[2:3], v[38:39]
	v_pk_mul_f32 v[36:37], v[0:1], v[36:37]
	ds_write_b128 v224, v[32:35]
	ds_write_b128 v224, v[36:39] offset:16
	v_lshl_add_u64 v[228:229], v[40:41], 0, v[226:227]
	s_waitcnt lgkmcnt(0)
	s_barrier
	ds_read_b128 v[230:233], v225
	ds_read_b128 v[234:237], v225 offset:1040
	s_waitcnt lgkmcnt(0)
	s_barrier
	global_store_dwordx4 v[228:229], v[230:233], off offset:-2048
	global_store_dwordx4 v[228:229], v[234:237], off offset:2048
	v_add_u32_e32 v40, s14, v81
	v_ashrrev_i32_e32 v41, 31, v40
	v_lshlrev_b64 v[40:41], 12, v[40:41]
	s_waitcnt lgkmcnt(5)
	v_pk_mul_f32 v[32:33], v[48:49], v[82:83] op_sel_hi:[1,0]
	v_pk_mul_f32 v[34:35], v[50:51], v[82:83] op_sel_hi:[1,0]
	v_lshl_add_u64 v[40:41], s[76:77], 0, v[40:41]
	v_pk_mul_f32 v[34:35], v[6:7], v[34:35]
	v_pk_mul_f32 v[32:33], v[4:5], v[32:33]
	v_pk_mul_f32 v[36:37], v[52:53], v[82:83] op_sel_hi:[1,0]
	v_pk_mul_f32 v[38:39], v[54:55], v[82:83] op_sel_hi:[1,0]
	v_lshl_add_u64 v[40:41], v[40:41], 0, v[72:73]
	v_pk_mul_f32 v[38:39], v[2:3], v[38:39]
	v_pk_mul_f32 v[36:37], v[0:1], v[36:37]
	ds_write_b128 v224, v[32:35]
	ds_write_b128 v224, v[36:39] offset:16
	v_lshl_add_u64 v[228:229], v[40:41], 0, v[226:227]
	s_waitcnt lgkmcnt(0)
	s_barrier
	ds_read_b128 v[230:233], v225
	ds_read_b128 v[234:237], v225 offset:1040
	s_waitcnt lgkmcnt(0)
	s_barrier
	global_store_dwordx4 v[228:229], v[230:233], off offset:-2048
	global_store_dwordx4 v[228:229], v[234:237], off offset:2048
	v_add_u32_e32 v40, s14, v83
	v_ashrrev_i32_e32 v41, 31, v40
	v_lshlrev_b64 v[40:41], 12, v[40:41]
	s_waitcnt lgkmcnt(4)
	v_pk_mul_f32 v[32:33], v[56:57], v[84:85] op_sel_hi:[1,0]
	v_pk_mul_f32 v[34:35], v[58:59], v[84:85] op_sel_hi:[1,0]
	v_lshl_add_u64 v[40:41], s[76:77], 0, v[40:41]
	v_pk_mul_f32 v[34:35], v[6:7], v[34:35]
	v_pk_mul_f32 v[32:33], v[4:5], v[32:33]
	v_pk_mul_f32 v[36:37], v[60:61], v[84:85] op_sel_hi:[1,0]
	v_pk_mul_f32 v[38:39], v[62:63], v[84:85] op_sel_hi:[1,0]
	v_lshl_add_u64 v[40:41], v[40:41], 0, v[72:73]
	v_pk_mul_f32 v[38:39], v[2:3], v[38:39]
	v_pk_mul_f32 v[36:37], v[0:1], v[36:37]
	ds_write_b128 v224, v[32:35]
	ds_write_b128 v224, v[36:39] offset:16
	v_lshl_add_u64 v[228:229], v[40:41], 0, v[226:227]
	s_waitcnt lgkmcnt(0)
	s_barrier
	ds_read_b128 v[230:233], v225
	ds_read_b128 v[234:237], v225 offset:1040
	s_waitcnt lgkmcnt(0)
	s_barrier
	global_store_dwordx4 v[228:229], v[230:233], off offset:-2048
	global_store_dwordx4 v[228:229], v[234:237], off offset:2048
	s_waitcnt lgkmcnt(3)
	v_pk_mul_f32 v[8:9], v[8:9], v[86:87] op_sel_hi:[1,0]
	v_add_u32_e32 v32, s14, v76
	v_ashrrev_i32_e32 v33, 31, v32
	v_lshlrev_b64 v[32:33], 12, v[32:33]
	v_pk_mul_f32 v[10:11], v[10:11], v[86:87] op_sel_hi:[1,0]
	v_lshl_add_u64 v[32:33], s[76:77], 0, v[32:33]
	v_pk_mul_f32 v[10:11], v[6:7], v[10:11]
	v_pk_mul_f32 v[8:9], v[4:5], v[8:9]
	v_pk_mul_f32 v[12:13], v[12:13], v[86:87] op_sel_hi:[1,0]
	v_pk_mul_f32 v[14:15], v[14:15], v[86:87] op_sel_hi:[1,0]
	v_lshl_add_u64 v[32:33], v[32:33], 0, v[72:73]
	v_pk_mul_f32 v[14:15], v[2:3], v[14:15]
	v_pk_mul_f32 v[12:13], v[0:1], v[12:13]
	ds_write_b128 v224, v[8:11]
	ds_write_b128 v224, v[12:15] offset:16
	v_lshl_add_u64 v[228:229], v[32:33], 0, v[226:227]
	s_waitcnt lgkmcnt(0)
	s_barrier
	ds_read_b128 v[230:233], v225
	ds_read_b128 v[234:237], v225 offset:1040
	s_waitcnt lgkmcnt(0)
	s_barrier
	global_store_dwordx4 v[228:229], v[230:233], off offset:-2048
	global_store_dwordx4 v[228:229], v[234:237], off offset:2048
	v_add_u32_e32 v32, s14, v87
	v_ashrrev_i32_e32 v33, 31, v32
	s_waitcnt lgkmcnt(2)
	v_pk_mul_f32 v[8:9], v[16:17], v[88:89] op_sel_hi:[1,0]
	v_lshlrev_b64 v[16:17], 12, v[32:33]
	v_pk_mul_f32 v[10:11], v[18:19], v[88:89] op_sel_hi:[1,0]
	v_lshl_add_u64 v[16:17], s[76:77], 0, v[16:17]
	v_pk_mul_f32 v[10:11], v[6:7], v[10:11]
	v_pk_mul_f32 v[8:9], v[4:5], v[8:9]
	v_pk_mul_f32 v[12:13], v[20:21], v[88:89] op_sel_hi:[1,0]
	v_pk_mul_f32 v[14:15], v[22:23], v[88:89] op_sel_hi:[1,0]
	v_lshl_add_u64 v[16:17], v[16:17], 0, v[72:73]
	v_pk_mul_f32 v[14:15], v[2:3], v[14:15]
	v_pk_mul_f32 v[12:13], v[0:1], v[12:13]
	ds_write_b128 v224, v[8:11]
	ds_write_b128 v224, v[12:15] offset:16
	v_lshl_add_u64 v[228:229], v[16:17], 0, v[226:227]
	s_waitcnt lgkmcnt(0)
	s_barrier
	ds_read_b128 v[230:233], v225
	ds_read_b128 v[234:237], v225 offset:1040
	s_waitcnt lgkmcnt(0)
	s_barrier
	global_store_dwordx4 v[228:229], v[230:233], off offset:-2048
	global_store_dwordx4 v[228:229], v[234:237], off offset:2048
	v_add_u32_e32 v16, s14, v89
	v_ashrrev_i32_e32 v17, 31, v16
	v_lshlrev_b64 v[16:17], 12, v[16:17]
	s_waitcnt lgkmcnt(1)
	v_pk_mul_f32 v[8:9], v[24:25], v[90:91] op_sel_hi:[1,0]
	v_pk_mul_f32 v[10:11], v[26:27], v[90:91] op_sel_hi:[1,0]
	v_lshl_add_u64 v[16:17], s[76:77], 0, v[16:17]
	v_pk_mul_f32 v[10:11], v[6:7], v[10:11]
	v_pk_mul_f32 v[8:9], v[4:5], v[8:9]
	v_pk_mul_f32 v[12:13], v[28:29], v[90:91] op_sel_hi:[1,0]
	v_pk_mul_f32 v[14:15], v[30:31], v[90:91] op_sel_hi:[1,0]
	v_lshl_add_u64 v[16:17], v[16:17], 0, v[72:73]
	v_pk_mul_f32 v[14:15], v[2:3], v[14:15]
	v_pk_mul_f32 v[12:13], v[0:1], v[12:13]
	ds_write_b128 v224, v[8:11]
	ds_write_b128 v224, v[12:15] offset:16
	v_lshl_add_u64 v[228:229], v[16:17], 0, v[226:227]
	s_waitcnt lgkmcnt(0)
	s_barrier
	ds_read_b128 v[230:233], v225
	ds_read_b128 v[234:237], v225 offset:1040
	s_waitcnt lgkmcnt(0)
	s_barrier
	global_store_dwordx4 v[228:229], v[230:233], off offset:-2048
	global_store_dwordx4 v[228:229], v[234:237], off offset:2048
	s_nop 0
	v_add_u32_e32 v8, s14, v91
	v_ashrrev_i32_e32 v9, 31, v8
	s_waitcnt lgkmcnt(0)
	v_pk_mul_f32 v[10:11], v[68:69], v[92:93] op_sel_hi:[1,0]
	v_pk_mul_f32 v[12:13], v[64:65], v[92:93] op_sel_hi:[1,0]
	v_lshlrev_b64 v[8:9], 12, v[8:9]
	v_pk_mul_f32 v[6:7], v[6:7], v[12:13]
	v_pk_mul_f32 v[4:5], v[4:5], v[10:11]
	v_pk_mul_f32 v[10:11], v[70:71], v[92:93] op_sel_hi:[1,0]
	v_pk_mul_f32 v[12:13], v[66:67], v[92:93] op_sel_hi:[1,0]
	v_lshl_add_u64 v[8:9], s[76:77], 0, v[8:9]
	v_pk_mul_f32 v[2:3], v[2:3], v[12:13]
	v_pk_mul_f32 v[0:1], v[0:1], v[10:11]
	v_lshl_add_u64 v[8:9], v[8:9], 0, v[72:73]
	ds_write_b128 v224, v[4:7]
	ds_write_b128 v224, v[0:3] offset:16
	v_lshl_add_u64 v[228:229], v[8:9], 0, v[226:227]
	s_waitcnt lgkmcnt(0)
	s_barrier
	ds_read_b128 v[230:233], v225
	ds_read_b128 v[234:237], v225 offset:1040
	s_waitcnt lgkmcnt(0)
	s_barrier
	global_store_dwordx4 v[228:229], v[230:233], off offset:-2048
	global_store_dwordx4 v[228:229], v[234:237], off offset:2048
	s_cbranch_scc1 .LBB0_2014
